# nt hint also on the final f32 output stores of P8
# baseline (speedup 1.0000x reference)
;     __device__ __forceinline__ void operator()(Acc& acc, const Unit& u, int wr, int wc, int fr, int fq) const {
;     ...
;         const f32x4 g00 = *(const f32x4*)(gain + col0), g01 = *(const f32x4*)(gain + col0 + 4), g10 = *(const f32x4*)(gain + col0 + HALF), g11 = *(const f32x4*)(gain + col0 + HALF + 4);
; #pragma unroll
;         for (int ai = 0; ai < 2; ++ai)
; #pragma unroll
;             for (int m = 0; m < 4; ++m) {
;                 const int row = row0 + ai * HALF + m * 16;
;                 const float r = rsqrtf(__hip_atomic_load(ss + row, __ATOMIC_RELAXED, __HIP_MEMORY_SCOPE_AGENT) * (1.0f / DM) + NORM_EPS);
;                 float* op = out + (size_t)row * DM + col0;
;                 *(f32x4*)op = acc[ai][0][m][0] * r * g00; *(f32x4*)(op + 4) = acc[ai][0][m][1] * r * g01;
;                 *(f32x4*)(op + HALF) = acc[ai][1][m][0] * r * g10; *(f32x4*)(op + HALF + 4) = acc[ai][1][m][1] * r * g11;
;             }
.LBB0_1752:
	v_lshlrev_b64 v[80:81], 2, v[176:177]
	v_lshl_add_u64 v[8:9], s[86:87], 0, v[80:81]
	global_load_dwordx4 v[4:7], v[8:9], off offset:16
	global_load_dwordx4 v[12:15], v[8:9], off
	s_waitcnt lgkmcnt(0)
	global_load_dwordx4 v[0:3], v[8:9], off offset:528
	s_nop 0
	global_load_dwordx4 v[8:11], v[8:9], off offset:512
	global_load_dword v204, v[112:113], off sc1
	global_load_dword v205, v[188:189], off sc1
	global_load_dword v206, v[190:191], off sc1
	global_load_dword v207, v[192:193], off sc1
	global_load_dword v208, v[112:113], off offset:512 sc1
	global_load_dword v209, v[112:113], off offset:576 sc1
	global_load_dword v210, v[112:113], off offset:640 sc1
	global_load_dword v211, v[112:113], off offset:704 sc1
	s_nop 0
	s_waitcnt vmcnt(0)
	v_fmamk_f32 v82, v204, 0x3a800000, v203
	v_mul_f32_e32 v83, 0x4b800000, v82
	v_cmp_gt_f32_e32 vcc, s43, v82
	s_nop 1
	v_cndmask_b32_e32 v82, v82, v83, vcc
	v_rsq_f32_e32 v84, v82
	v_lshlrev_b64 v[82:83], 12, v[174:175]
	v_lshl_add_u64 v[82:83], s[72:73], 0, v[82:83]
	v_lshl_add_u64 v[86:87], v[82:83], 0, v[80:81]
	v_mul_f32_e32 v82, 0x45800000, v84
	v_cndmask_b32_e32 v82, v84, v82, vcc
	v_pk_mul_f32 v[174:175], v[178:179], v[82:83] op_sel_hi:[1,0]
	v_pk_mul_f32 v[84:85], v[126:127], v[82:83] op_sel_hi:[1,0]
	v_pk_mul_f32 v[124:125], v[124:125], v[82:83] op_sel_hi:[1,0]
	v_pk_mul_f32 v[122:123], v[122:123], v[82:83] op_sel_hi:[1,0]
	v_pk_mul_f32 v[126:127], v[120:121], v[82:83] op_sel_hi:[1,0]
	v_pk_mul_f32 v[118:119], v[118:119], v[82:83] op_sel_hi:[1,0]
	v_pk_mul_f32 v[176:177], v[116:117], v[82:83] op_sel_hi:[1,0]
	v_pk_mul_f32 v[178:179], v[114:115], v[82:83] op_sel_hi:[1,0]
	v_pk_mul_f32 v[84:85], v[14:15], v[84:85]
	v_pk_mul_f32 v[82:83], v[12:13], v[174:175]
	v_pk_mul_f32 v[116:117], v[6:7], v[122:123]
	v_pk_mul_f32 v[114:115], v[4:5], v[124:125]
	v_pk_mul_f32 v[120:121], v[10:11], v[118:119]
	v_pk_mul_f32 v[118:119], v[8:9], v[126:127]
	v_pk_mul_f32 v[124:125], v[2:3], v[178:179]
	v_pk_mul_f32 v[122:123], v[0:1], v[176:177]
	global_store_dwordx4 v[86:87], v[82:85], off nt
	global_store_dwordx4 v[86:87], v[114:117], off offset:16 nt
	global_store_dwordx4 v[86:87], v[118:121], off offset:512 nt
	global_store_dwordx4 v[86:87], v[122:125], off offset:528 nt
	s_nop 1
	v_fmamk_f32 v82, v205, 0x3a800000, v203
	v_mul_f32_e32 v83, 0x4b800000, v82
	v_cmp_gt_f32_e32 vcc, s43, v82
	s_nop 1
	v_cndmask_b32_e32 v82, v82, v83, vcc
	v_rsq_f32_e32 v84, v82
	v_lshlrev_b64 v[82:83], 12, v[172:173]
	v_lshl_add_u64 v[82:83], s[72:73], 0, v[82:83]
	v_lshl_add_u64 v[86:87], v[82:83], 0, v[80:81]
	v_mul_f32_e32 v82, 0x45800000, v84
	v_cndmask_b32_e32 v82, v84, v82, vcc
	v_pk_mul_f32 v[108:109], v[108:109], v[82:83] op_sel_hi:[1,0]
	v_pk_mul_f32 v[84:85], v[110:111], v[82:83] op_sel_hi:[1,0]
	v_pk_mul_f32 v[104:105], v[104:105], v[82:83] op_sel_hi:[1,0]
	v_pk_mul_f32 v[106:107], v[106:107], v[82:83] op_sel_hi:[1,0]
	v_pk_mul_f32 v[100:101], v[100:101], v[82:83] op_sel_hi:[1,0]
	v_pk_mul_f32 v[102:103], v[102:103], v[82:83] op_sel_hi:[1,0]
	v_pk_mul_f32 v[110:111], v[96:97], v[82:83] op_sel_hi:[1,0]
	v_pk_mul_f32 v[114:115], v[98:99], v[82:83] op_sel_hi:[1,0]
	v_pk_mul_f32 v[84:85], v[14:15], v[84:85]
	v_pk_mul_f32 v[82:83], v[12:13], v[108:109]
	v_pk_mul_f32 v[98:99], v[6:7], v[106:107]
	v_pk_mul_f32 v[96:97], v[4:5], v[104:105]
	v_pk_mul_f32 v[102:103], v[10:11], v[102:103]
	v_pk_mul_f32 v[100:101], v[8:9], v[100:101]
	v_pk_mul_f32 v[106:107], v[2:3], v[114:115]
	v_pk_mul_f32 v[104:105], v[0:1], v[110:111]
	global_store_dwordx4 v[86:87], v[82:85], off nt
	global_store_dwordx4 v[86:87], v[96:99], off offset:16 nt
	global_store_dwordx4 v[86:87], v[100:103], off offset:512 nt
	global_store_dwordx4 v[86:87], v[104:107], off offset:528 nt
	s_nop 1
	v_fmamk_f32 v82, v206, 0x3a800000, v203
	v_mul_f32_e32 v83, 0x4b800000, v82
	v_cmp_gt_f32_e32 vcc, s43, v82
	s_nop 1
	v_cndmask_b32_e32 v82, v82, v83, vcc
	v_rsq_f32_e32 v84, v82
	v_lshlrev_b64 v[82:83], 12, v[170:171]
	v_lshl_add_u64 v[82:83], s[72:73], 0, v[82:83]
	v_lshl_add_u64 v[86:87], v[82:83], 0, v[80:81]
	v_mul_f32_e32 v82, 0x45800000, v84
	v_cndmask_b32_e32 v82, v84, v82, vcc
	v_pk_mul_f32 v[96:97], v[144:145], v[82:83] op_sel_hi:[1,0]
	v_pk_mul_f32 v[84:85], v[94:95], v[82:83] op_sel_hi:[1,0]
	v_pk_mul_f32 v[94:95], v[142:143], v[82:83] op_sel_hi:[1,0]
	v_pk_mul_f32 v[98:99], v[140:141], v[82:83] op_sel_hi:[1,0]
	v_pk_mul_f32 v[102:103], v[146:147], v[82:83] op_sel_hi:[1,0]
	v_pk_mul_f32 v[100:101], v[136:137], v[82:83] op_sel_hi:[1,0]
	v_pk_mul_f32 v[106:107], v[148:149], v[82:83] op_sel_hi:[1,0]
	v_pk_mul_f32 v[104:105], v[138:139], v[82:83] op_sel_hi:[1,0]
	v_pk_mul_f32 v[84:85], v[14:15], v[84:85]
	v_pk_mul_f32 v[82:83], v[12:13], v[96:97]
	v_pk_mul_f32 v[96:97], v[6:7], v[98:99]
	v_pk_mul_f32 v[94:95], v[4:5], v[94:95]
	v_pk_mul_f32 v[100:101], v[10:11], v[100:101]
	v_pk_mul_f32 v[98:99], v[8:9], v[102:103]
	v_pk_mul_f32 v[104:105], v[2:3], v[104:105]
	v_pk_mul_f32 v[102:103], v[0:1], v[106:107]
	global_store_dwordx4 v[86:87], v[82:85], off nt
	global_store_dwordx4 v[86:87], v[94:97], off offset:16 nt
	global_store_dwordx4 v[86:87], v[98:101], off offset:512 nt
	global_store_dwordx4 v[86:87], v[102:105], off offset:528 nt
	s_nop 1
	v_fmamk_f32 v82, v207, 0x3a800000, v203
	v_mul_f32_e32 v83, 0x4b800000, v82
	v_cmp_gt_f32_e32 vcc, s43, v82
	s_nop 1
	v_cndmask_b32_e32 v82, v82, v83, vcc
	v_rsq_f32_e32 v84, v82
	v_lshlrev_b64 v[82:83], 12, v[168:169]
	v_lshl_add_u64 v[82:83], s[72:73], 0, v[82:83]
	v_lshl_add_u64 v[86:87], v[82:83], 0, v[80:81]
	v_mul_f32_e32 v82, 0x45800000, v84
	v_cndmask_b32_e32 v82, v84, v82, vcc
	v_pk_mul_f32 v[94:95], v[150:151], v[82:83] op_sel_hi:[1,0]
;     __device__ __forceinline__ void operator()(Acc& acc, const Unit& u, int wr, int wc, int fr, int fq) const {
;     ...
;         for (int ai = 0; ai < 2; ++ai)
; #pragma unroll
;             for (int m = 0; m < 4; ++m) {
;                 const int row = row0 + ai * HALF + m * 16;
;                 const float r = rsqrtf(__hip_atomic_load(ss + row, __ATOMIC_RELAXED, __HIP_MEMORY_SCOPE_AGENT) * (1.0f / DM) + NORM_EPS);
;                 float* op = out + (size_t)row * DM + col0;
;                 *(f32x4*)op = acc[ai][0][m][0] * r * g00; *(f32x4*)(op + 4) = acc[ai][0][m][1] * r * g01;
;                 *(f32x4*)(op + HALF) = acc[ai][1][m][0] * r * g10; *(f32x4*)(op + HALF + 4) = acc[ai][1][m][1] * r * g11;
;             }
	v_pk_mul_f32 v[84:85], v[132:133], v[82:83] op_sel_hi:[1,0]
	v_pk_mul_f32 v[98:99], v[180:181], v[82:83] op_sel_hi:[1,0]
	v_pk_mul_f32 v[96:97], v[134:135], v[82:83] op_sel_hi:[1,0]
	v_pk_mul_f32 v[102:103], v[182:183], v[82:83] op_sel_hi:[1,0]
	v_pk_mul_f32 v[100:101], v[128:129], v[82:83] op_sel_hi:[1,0]
	v_pk_mul_f32 v[106:107], v[184:185], v[82:83] op_sel_hi:[1,0]
	v_pk_mul_f32 v[104:105], v[130:131], v[82:83] op_sel_hi:[1,0]
	v_pk_mul_f32 v[84:85], v[14:15], v[84:85]
	v_pk_mul_f32 v[82:83], v[12:13], v[94:95]
	v_pk_mul_f32 v[96:97], v[6:7], v[96:97]
	v_pk_mul_f32 v[94:95], v[4:5], v[98:99]
	v_pk_mul_f32 v[100:101], v[10:11], v[100:101]
	v_pk_mul_f32 v[98:99], v[8:9], v[102:103]
	v_pk_mul_f32 v[104:105], v[2:3], v[104:105]
	v_pk_mul_f32 v[102:103], v[0:1], v[106:107]
	global_store_dwordx4 v[86:87], v[82:85], off nt
	global_store_dwordx4 v[86:87], v[94:97], off offset:16 nt
	global_store_dwordx4 v[86:87], v[98:101], off offset:512 nt
	global_store_dwordx4 v[86:87], v[102:105], off offset:528 nt
	s_nop 1
	v_fmamk_f32 v82, v208, 0x3a800000, v203
	v_mul_f32_e32 v83, 0x4b800000, v82
	v_cmp_gt_f32_e32 vcc, s43, v82
	s_nop 1
	v_cndmask_b32_e32 v82, v82, v83, vcc
	v_rsq_f32_e32 v84, v82
	v_lshlrev_b64 v[82:83], 12, v[186:187]
	v_lshl_add_u64 v[82:83], s[72:73], 0, v[82:83]
	v_lshl_add_u64 v[82:83], v[82:83], 0, v[80:81]
	v_mul_f32_e32 v85, 0x45800000, v84
	v_cndmask_b32_e32 v84, v84, v85, vcc
	v_pk_mul_f32 v[60:61], v[60:61], v[84:85] op_sel_hi:[1,0]
	v_pk_mul_f32 v[62:63], v[62:63], v[84:85] op_sel_hi:[1,0]
	v_pk_mul_f32 v[56:57], v[56:57], v[84:85] op_sel_hi:[1,0]
	v_pk_mul_f32 v[58:59], v[58:59], v[84:85] op_sel_hi:[1,0]
	v_pk_mul_f32 v[86:87], v[52:53], v[84:85] op_sel_hi:[1,0]
	v_pk_mul_f32 v[94:95], v[54:55], v[84:85] op_sel_hi:[1,0]
	v_pk_mul_f32 v[96:97], v[48:49], v[84:85] op_sel_hi:[1,0]
	v_pk_mul_f32 v[84:85], v[50:51], v[84:85] op_sel_hi:[1,0]
	v_pk_mul_f32 v[50:51], v[14:15], v[62:63]
	v_pk_mul_f32 v[48:49], v[12:13], v[60:61]
	v_pk_mul_f32 v[54:55], v[6:7], v[58:59]
	v_pk_mul_f32 v[52:53], v[4:5], v[56:57]
	v_pk_mul_f32 v[58:59], v[10:11], v[94:95]
	v_pk_mul_f32 v[56:57], v[8:9], v[86:87]
	v_pk_mul_f32 v[62:63], v[2:3], v[84:85]
	v_pk_mul_f32 v[60:61], v[0:1], v[96:97]
	global_store_dwordx4 v[82:83], v[48:51], off nt
	global_store_dwordx4 v[82:83], v[52:55], off offset:16 nt
	global_store_dwordx4 v[82:83], v[56:59], off offset:512 nt
	global_store_dwordx4 v[82:83], v[60:63], off offset:528 nt
	s_nop 1
	v_fmamk_f32 v48, v209, 0x3a800000, v203
	v_mul_f32_e32 v49, 0x4b800000, v48
	v_cmp_gt_f32_e32 vcc, s43, v48
	s_nop 1
	v_cndmask_b32_e32 v48, v48, v49, vcc
	v_rsq_f32_e32 v50, v48
	v_lshlrev_b64 v[48:49], 12, v[92:93]
	v_lshl_add_u64 v[48:49], s[72:73], 0, v[48:49]
	v_lshl_add_u64 v[48:49], v[48:49], 0, v[80:81]
	v_mul_f32_e32 v51, 0x45800000, v50
	v_cndmask_b32_e32 v50, v50, v51, vcc
	v_pk_mul_f32 v[44:45], v[44:45], v[50:51] op_sel_hi:[1,0]
	v_pk_mul_f32 v[46:47], v[46:47], v[50:51] op_sel_hi:[1,0]
	v_pk_mul_f32 v[40:41], v[40:41], v[50:51] op_sel_hi:[1,0]
	v_pk_mul_f32 v[42:43], v[42:43], v[50:51] op_sel_hi:[1,0]
	v_pk_mul_f32 v[52:53], v[36:37], v[50:51] op_sel_hi:[1,0]
	v_pk_mul_f32 v[54:55], v[38:39], v[50:51] op_sel_hi:[1,0]
	v_pk_mul_f32 v[56:57], v[32:33], v[50:51] op_sel_hi:[1,0]
	v_pk_mul_f32 v[50:51], v[34:35], v[50:51] op_sel_hi:[1,0]
	v_pk_mul_f32 v[34:35], v[14:15], v[46:47]
	v_pk_mul_f32 v[32:33], v[12:13], v[44:45]
	v_pk_mul_f32 v[38:39], v[6:7], v[42:43]
	v_pk_mul_f32 v[36:37], v[4:5], v[40:41]
	v_pk_mul_f32 v[42:43], v[10:11], v[54:55]
	v_pk_mul_f32 v[40:41], v[8:9], v[52:53]
	v_pk_mul_f32 v[46:47], v[2:3], v[50:51]
	v_pk_mul_f32 v[44:45], v[0:1], v[56:57]
	global_store_dwordx4 v[48:49], v[32:35], off nt
	global_store_dwordx4 v[48:49], v[36:39], off offset:16 nt
	global_store_dwordx4 v[48:49], v[40:43], off offset:512 nt
	global_store_dwordx4 v[48:49], v[44:47], off offset:528 nt
	s_nop 1
	v_fmamk_f32 v32, v210, 0x3a800000, v203
	v_mul_f32_e32 v33, 0x4b800000, v32
	v_cmp_gt_f32_e32 vcc, s43, v32
	s_nop 1
	v_cndmask_b32_e32 v32, v32, v33, vcc
	v_rsq_f32_e32 v34, v32
	v_lshlrev_b64 v[32:33], 12, v[90:91]
	v_lshl_add_u64 v[32:33], s[72:73], 0, v[32:33]
	v_lshl_add_u64 v[40:41], v[32:33], 0, v[80:81]
	v_mul_f32_e32 v32, 0x45800000, v34
	v_cndmask_b32_e32 v32, v34, v32, vcc
	v_pk_mul_f32 v[28:29], v[28:29], v[32:33] op_sel_hi:[1,0]
	v_pk_mul_f32 v[30:31], v[30:31], v[32:33] op_sel_hi:[1,0]
	v_pk_mul_f32 v[34:35], v[24:25], v[32:33] op_sel_hi:[1,0]
	v_pk_mul_f32 v[36:37], v[26:27], v[32:33] op_sel_hi:[1,0]
	v_pk_mul_f32 v[38:39], v[76:77], v[32:33] op_sel_hi:[1,0]
	v_pk_mul_f32 v[42:43], v[72:73], v[32:33] op_sel_hi:[1,0]
	v_pk_mul_f32 v[44:45], v[78:79], v[32:33] op_sel_hi:[1,0]
	v_pk_mul_f32 v[46:47], v[74:75], v[32:33] op_sel_hi:[1,0]
	v_pk_mul_f32 v[26:27], v[14:15], v[30:31]
	v_pk_mul_f32 v[24:25], v[12:13], v[28:29]
	v_pk_mul_f32 v[30:31], v[6:7], v[36:37]
	v_pk_mul_f32 v[28:29], v[4:5], v[34:35]
	v_pk_mul_f32 v[34:35], v[10:11], v[42:43]
	v_pk_mul_f32 v[32:33], v[8:9], v[38:39]
	v_pk_mul_f32 v[38:39], v[2:3], v[46:47]
	v_pk_mul_f32 v[36:37], v[0:1], v[44:45]
	global_store_dwordx4 v[40:41], v[24:27], off nt
	global_store_dwordx4 v[40:41], v[28:31], off offset:16 nt
	global_store_dwordx4 v[40:41], v[32:35], off offset:512 nt
	global_store_dwordx4 v[40:41], v[36:39], off offset:528 nt
	v_lshlrev_b64 v[24:25], 12, v[88:89]
	v_lshl_add_u64 v[24:25], s[72:73], 0, v[24:25]
	s_and_b64 vcc, exec, s[4:5]
	v_lshl_add_u64 v[24:25], v[24:25], 0, v[80:81]
	s_mov_b64 s[4:5], -1
	s_nop 1
	v_fmamk_f32 v26, v211, 0x3a800000, v203
	v_mul_f32_e32 v27, 0x4b800000, v26
	v_cmp_gt_f32_e64 s[6:7], s43, v26
	s_nop 1
	v_cndmask_b32_e64 v26, v26, v27, s[6:7]
	v_rsq_f32_e32 v26, v26
	s_nop 0
	v_mul_f32_e32 v27, 0x45800000, v26
	v_cndmask_b32_e64 v26, v26, v27, s[6:7]
	v_pk_mul_f32 v[18:19], v[18:19], v[26:27] op_sel_hi:[1,0]
	v_pk_mul_f32 v[16:17], v[16:17], v[26:27] op_sel_hi:[1,0]
	v_pk_mul_f32 v[22:23], v[22:23], v[26:27] op_sel_hi:[1,0]
	v_pk_mul_f32 v[20:21], v[20:21], v[26:27] op_sel_hi:[1,0]
	v_pk_mul_f32 v[28:29], v[68:69], v[26:27] op_sel_hi:[1,0]
	v_pk_mul_f32 v[30:31], v[64:65], v[26:27] op_sel_hi:[1,0]
	v_pk_mul_f32 v[32:33], v[70:71], v[26:27] op_sel_hi:[1,0]
	v_pk_mul_f32 v[26:27], v[66:67], v[26:27] op_sel_hi:[1,0]
	v_pk_mul_f32 v[14:15], v[14:15], v[16:17]
	v_pk_mul_f32 v[12:13], v[12:13], v[18:19]
	v_pk_mul_f32 v[6:7], v[6:7], v[20:21]
	v_pk_mul_f32 v[4:5], v[4:5], v[22:23]
	v_pk_mul_f32 v[10:11], v[10:11], v[30:31]
	v_pk_mul_f32 v[8:9], v[8:9], v[28:29]
	v_pk_mul_f32 v[2:3], v[2:3], v[26:27]
	v_pk_mul_f32 v[0:1], v[0:1], v[32:33]
	global_store_dwordx4 v[24:25], v[12:15], off nt
	global_store_dwordx4 v[24:25], v[4:7], off offset:16 nt
	global_store_dwordx4 v[24:25], v[8:11], off offset:512 nt
	global_store_dwordx4 v[24:25], v[0:3], off offset:528 nt
	s_mov_b32 s101, 1
	s_cbranch_vccnz .LBB0_1710
	s_andn2_b64 vcc, exec, s[8:9]
	s_cbranch_vccnz .LBB0_1709
	s_barrier
	s_branch .LBB0_1709
